# P4 attention no-mask steps of gathered loops: hand-written step, scores stay in MFMA result regs, v_pk_fma_f32 scale/shift, v_pk_add_f32 row-sum tree, bookkeeping in MFMA latency slot
# speedup vs baseline: 1.0034x; 1.0034x over previous
; DI unsigned pack2bf(float a, float b) { const f2_t v = {a, b}; return __builtin_bit_cast(unsigned, __builtin_convertvector(v, bf2_t)); }
; DI float xor32_max(float v) { const auto r = __builtin_amdgcn_permlane32_swap(__float_as_uint(v), __float_as_uint(v), false, false); return fmaxf(__uint_as_float(r[0]), __uint_as_float(r[1])); }
; DI void attn_task(const Params& P, int bh, int n, int t, int lane, const char* Ks, const char* Vs) {
;     ...
; #pragma unroll
;     for (int s = 0; s < 4; ++s) {
;       const bf16x8 kf = *reinterpret_cast<const bf16x8*>(Ks + krow * 128 + (((2 * s + hh) ^ ((krow >> 1) & 7)) * 16));
;       S = __builtin_amdgcn_mfma_f32_32x32x16_bf16(kf, qf[s], S, 0, 0, 0);
;     }
;     const bool diag = own && (kt == t);
;     constexpr float SC2 = 0.125f * 1.4426950408889634f;
;     float mx = -1e30f;
; #pragma unroll
;     for (int i = 0; i < 16; ++i) {
;       if (diag && (kbase + crow(i, hh) > lq)) S[i] = -1e30f;
;       mx = fmaxf(mx, S[i]);
;     }
;     mx = xor32_max(mx);
;     const float m_new = fmaxf(m_run, mx * SC2);
;     const float alpha = __builtin_amdgcn_exp2f(m_run - m_new);
;     float rs = 0.f;
; #pragma unroll
;     for (int i = 0; i < 16; ++i) { float pv = __builtin_amdgcn_exp2f(fmaf(S[i], SC2, -m_new)); S[i] = pv; rs += pv; }
;     rs = xor32_sum(rs);
;     l_run = l_run * alpha + rs; m_run = m_new;
;     if (__ballot(alpha != 1.f)) {
; #pragma unroll
;       for (int i = 0; i < 16; ++i) { O0[i] *= alpha; O1[i] *= alpha; }
;     }
; #pragma unroll
;     for (int s = 0; s < 2; ++s) {
;       const uint4 ppk = make_uint4(pack2bf(S[8 * s], S[8 * s + 1]), pack2bf(S[8 * s + 2], S[8 * s + 3]), pack2bf(S[8 * s + 4], S[8 * s + 5]), pack2bf(S[8 * s + 6], S[8 * s + 7]));
;       const bf16x8 pf = __builtin_bit_cast(bf16x8, ppk);
; #pragma unroll
;       for (int dt = 0; dt < 2; ++dt) {
;         const char* vp = Vs + (dt * 32 + r) * 528 + (kt * 32 + 16 * s + 4 * hh) * 2;
;         const uint2 lo = *reinterpret_cast<const uint2*>(vp), hi = *reinterpret_cast<const uint2*>(vp + 16);
;         const uint4 vv = make_uint4(lo.x, lo.y, hi.x, hi.y);
;         if (dt == 0) O0 = __builtin_amdgcn_mfma_f32_32x32x16_bf16(__builtin_bit_cast(bf16x8, vv), pf, O0, 0, 0, 0);
;         else O1 = __builtin_amdgcn_mfma_f32_32x32x16_bf16(__builtin_bit_cast(bf16x8, vv), pf, O1, 0, 0, 0);
;       }
;     }
.Lattn_fast_783:
	s_waitcnt vmcnt(3) lgkmcnt(1)
	v_mfma_f32_32x32x16_bf16 v[48:63], v[2:5], v[64:67], 0
	v_add_u32_e32 v2, v150, v197
	ds_read_b128 v[2:5], v2
	s_waitcnt vmcnt(2) lgkmcnt(1)
	v_mfma_f32_32x32x16_bf16 v[48:63], v[6:9], v[68:71], v[48:63]
	ds_read_b128 v[6:9], v10
	v_add_u32_e32 v210, v153, v197
	v_add_u32_e32 v211, v154, v197
	ds_read2_b64 v[216:219], v210 offset1:2
	ds_read2_b64 v[220:223], v211 offset1:2
	ds_read2_b64 v[224:227], v210 offset0:4 offset1:6
	ds_read2_b64 v[228:231], v211 offset0:4 offset1:6
	s_waitcnt vmcnt(1) lgkmcnt(5)
	v_mfma_f32_32x32x16_bf16 v[48:63], v[2:5], v[72:75], v[48:63]
	s_waitcnt vmcnt(0) lgkmcnt(4)
	v_mfma_f32_32x32x16_bf16 v[48:63], v[6:9], v[76:79], v[48:63]
	s_add_i32 s8, s8, 32
	v_add_u32_e32 v154, 64, v154
	v_add_u32_e32 v153, 64, v153
	v_add_u32_e32 v152, 0x1000, v152
	v_add_u32_e32 v151, 0x1000, v151
	v_add_u32_e32 v150, 0x1000, v150
	v_add_u32_e32 v149, 0x1000, v149
	v_cmp_eq_u32_e32 vcc, s8, v146
	s_or_b64 s[50:51], vcc, s[50:51]
	s_nop 7
	v_max3_f32 v4, v48, s22, v49
	v_max3_f32 v4, v4, v50, v51
	v_max3_f32 v4, v4, v52, v53
	v_max3_f32 v4, v4, v54, v55
	v_max3_f32 v4, v4, v56, v57
	v_max3_f32 v4, v4, v58, v59
	v_max3_f32 v4, v4, v60, v61
	v_max3_f32 v4, v4, v62, v63
	v_mov_b32_e32 v10, v4
	s_nop 1
	v_permlane32_swap_b32_e32 v4, v10
	v_max_f32_e32 v4, v4, v10
	v_mul_f32_e32 v4, 0x3e38aa3b, v4
	v_max_f32_e32 v6, v147, v4
	v_sub_f32_e32 v0, v147, v6
	v_pk_fma_f32 v[48:49], v[48:49], s[22:23], v[6:7] op_sel:[0,1,0] op_sel_hi:[1,1,0] neg_lo:[0,0,1] neg_hi:[0,0,1]
	v_pk_fma_f32 v[50:51], v[50:51], s[22:23], v[6:7] op_sel:[0,1,0] op_sel_hi:[1,1,0] neg_lo:[0,0,1] neg_hi:[0,0,1]
	v_pk_fma_f32 v[52:53], v[52:53], s[22:23], v[6:7] op_sel:[0,1,0] op_sel_hi:[1,1,0] neg_lo:[0,0,1] neg_hi:[0,0,1]
	v_pk_fma_f32 v[54:55], v[54:55], s[22:23], v[6:7] op_sel:[0,1,0] op_sel_hi:[1,1,0] neg_lo:[0,0,1] neg_hi:[0,0,1]
	v_pk_fma_f32 v[56:57], v[56:57], s[22:23], v[6:7] op_sel:[0,1,0] op_sel_hi:[1,1,0] neg_lo:[0,0,1] neg_hi:[0,0,1]
	v_pk_fma_f32 v[58:59], v[58:59], s[22:23], v[6:7] op_sel:[0,1,0] op_sel_hi:[1,1,0] neg_lo:[0,0,1] neg_hi:[0,0,1]
	v_pk_fma_f32 v[60:61], v[60:61], s[22:23], v[6:7] op_sel:[0,1,0] op_sel_hi:[1,1,0] neg_lo:[0,0,1] neg_hi:[0,0,1]
	v_pk_fma_f32 v[62:63], v[62:63], s[22:23], v[6:7] op_sel:[0,1,0] op_sel_hi:[1,1,0] neg_lo:[0,0,1] neg_hi:[0,0,1]
	v_exp_f32_e32 v0, v0
	v_exp_f32_e32 v48, v48
	v_exp_f32_e32 v49, v49
	v_exp_f32_e32 v50, v50
	v_exp_f32_e32 v51, v51
	v_exp_f32_e32 v52, v52
	v_exp_f32_e32 v53, v53
	v_exp_f32_e32 v54, v54
	v_exp_f32_e32 v55, v55
	v_exp_f32_e32 v56, v56
	v_exp_f32_e32 v57, v57
	v_exp_f32_e32 v58, v58
	v_exp_f32_e32 v59, v59
	v_exp_f32_e32 v60, v60
	v_exp_f32_e32 v61, v61
	v_exp_f32_e32 v62, v62
	v_exp_f32_e32 v63, v63
	s_nop 0
	v_pk_add_f32 v[232:233], v[48:49], v[50:51]
	v_pk_add_f32 v[234:235], v[52:53], v[54:55]
	v_pk_add_f32 v[236:237], v[56:57], v[58:59]
	v_pk_add_f32 v[238:239], v[60:61], v[62:63]
	v_pk_add_f32 v[232:233], v[232:233], v[234:235]
	v_pk_add_f32 v[236:237], v[236:237], v[238:239]
	v_pk_add_f32 v[232:233], v[232:233], v[236:237]
	v_add_f32_e32 v2, v232, v233
	v_mov_b32_e32 v3, v2
	s_nop 1
	v_permlane32_swap_b32_e32 v2, v3
	v_mov_b32_e32 v147, v6
	v_cvt_pk_bf16_f32 v8, v48, v49
	v_cvt_pk_bf16_f32 v9, v50, v51
	v_cvt_pk_bf16_f32 v10, v52, v53
	v_cvt_pk_bf16_f32 v11, v54, v55
	v_cvt_pk_bf16_f32 v12, v56, v57
	v_cvt_pk_bf16_f32 v13, v58, v59
	v_cvt_pk_bf16_f32 v14, v60, v61
	v_cvt_pk_bf16_f32 v15, v62, v63
	v_add_f32_e32 v4, v2, v3
	v_fmac_f32_e32 v4, v155, v0
	v_cmp_neq_f32_e32 vcc, 1.0, v0
	s_cbranch_vccz .Lattn_fkeep_783
	v_pk_mul_f32 v[30:31], v[30:31], v[0:1] op_sel_hi:[1,0]
	v_pk_mul_f32 v[28:29], v[28:29], v[0:1] op_sel_hi:[1,0]
	v_pk_mul_f32 v[26:27], v[26:27], v[0:1] op_sel_hi:[1,0]
	v_pk_mul_f32 v[24:25], v[24:25], v[0:1] op_sel_hi:[1,0]
	v_pk_mul_f32 v[22:23], v[22:23], v[0:1] op_sel_hi:[1,0]
	v_pk_mul_f32 v[20:21], v[20:21], v[0:1] op_sel_hi:[1,0]
	v_pk_mul_f32 v[18:19], v[18:19], v[0:1] op_sel_hi:[1,0]
	v_pk_mul_f32 v[16:17], v[16:17], v[0:1] op_sel_hi:[1,0]
	v_pk_mul_f32 v[46:47], v[46:47], v[0:1] op_sel_hi:[1,0]
	v_pk_mul_f32 v[44:45], v[44:45], v[0:1] op_sel_hi:[1,0]
	v_pk_mul_f32 v[42:43], v[42:43], v[0:1] op_sel_hi:[1,0]
	v_pk_mul_f32 v[40:41], v[40:41], v[0:1] op_sel_hi:[1,0]
	v_pk_mul_f32 v[38:39], v[38:39], v[0:1] op_sel_hi:[1,0]
	v_pk_mul_f32 v[36:37], v[36:37], v[0:1] op_sel_hi:[1,0]
	v_pk_mul_f32 v[34:35], v[34:35], v[0:1] op_sel_hi:[1,0]
	v_pk_mul_f32 v[32:33], v[32:33], v[0:1] op_sel_hi:[1,0]
.Lattn_fkeep_783:
	s_waitcnt lgkmcnt(0)
	v_mfma_f32_32x32x16_bf16 v[16:31], v[216:219], v[8:11], v[16:31]
	v_mfma_f32_32x32x16_bf16 v[32:47], v[220:223], v[8:11], v[32:47]
	v_mfma_f32_32x32x16_bf16 v[16:31], v[224:227], v[12:15], v[16:31]
	v_mov_b32_e32 v155, v4
	v_mfma_f32_32x32x16_bf16 v[32:47], v[228:231], v[12:15], v[32:47]
	s_andn2_b64 exec, exec, s[50:51]
	s_cbranch_execz .LBB0_794
	s_branch .LBB0_783
; DI unsigned pack2bf(float a, float b) { const f2_t v = {a, b}; return __builtin_bit_cast(unsigned, __builtin_convertvector(v, bf2_t)); }
; DI float xor32_max(float v) { const auto r = __builtin_amdgcn_permlane32_swap(__float_as_uint(v), __float_as_uint(v), false, false); return fmaxf(__uint_as_float(r[0]), __uint_as_float(r[1])); }
; DI void attn_task(const Params& P, int bh, int n, int t, int lane, const char* Ks, const char* Vs) {
;     ...
; #pragma unroll
;     for (int s = 0; s < 4; ++s) {
;       const bf16x8 kf = *reinterpret_cast<const bf16x8*>(Ks + krow * 128 + (((2 * s + hh) ^ ((krow >> 1) & 7)) * 16));
;       S = __builtin_amdgcn_mfma_f32_32x32x16_bf16(kf, qf[s], S, 0, 0, 0);
;     }
;     const bool diag = own && (kt == t);
;     constexpr float SC2 = 0.125f * 1.4426950408889634f;
;     float mx = -1e30f;
; #pragma unroll
;     for (int i = 0; i < 16; ++i) {
;       if (diag && (kbase + crow(i, hh) > lq)) S[i] = -1e30f;
;       mx = fmaxf(mx, S[i]);
;     }
;     mx = xor32_max(mx);
;     const float m_new = fmaxf(m_run, mx * SC2);
;     const float alpha = __builtin_amdgcn_exp2f(m_run - m_new);
;     float rs = 0.f;
; #pragma unroll
;     for (int i = 0; i < 16; ++i) { float pv = __builtin_amdgcn_exp2f(fmaf(S[i], SC2, -m_new)); S[i] = pv; rs += pv; }
;     rs = xor32_sum(rs);
;     l_run = l_run * alpha + rs; m_run = m_new;
;     if (__ballot(alpha != 1.f)) {
; #pragma unroll
;       for (int i = 0; i < 16; ++i) { O0[i] *= alpha; O1[i] *= alpha; }
;     }
; #pragma unroll
;     for (int s = 0; s < 2; ++s) {
;       const uint4 ppk = make_uint4(pack2bf(S[8 * s], S[8 * s + 1]), pack2bf(S[8 * s + 2], S[8 * s + 3]), pack2bf(S[8 * s + 4], S[8 * s + 5]), pack2bf(S[8 * s + 6], S[8 * s + 7]));
;       const bf16x8 pf = __builtin_bit_cast(bf16x8, ppk);
; #pragma unroll
;       for (int dt = 0; dt < 2; ++dt) {
;         const char* vp = Vs + (dt * 32 + r) * 528 + (kt * 32 + 16 * s + 4 * hh) * 2;
;         const uint2 lo = *reinterpret_cast<const uint2*>(vp), hi = *reinterpret_cast<const uint2*>(vp + 16);
;         const uint4 vv = make_uint4(lo.x, lo.y, hi.x, hi.y);
;         if (dt == 0) O0 = __builtin_amdgcn_mfma_f32_32x32x16_bf16(__builtin_bit_cast(bf16x8, vv), pf, O0, 0, 0, 0);
;         else O1 = __builtin_amdgcn_mfma_f32_32x32x16_bf16(__builtin_bit_cast(bf16x8, vv), pf, O1, 0, 0, 0);
;       }
;     }
.Lattn_fast_790:
	s_waitcnt vmcnt(3) lgkmcnt(2)
	v_mfma_f32_32x32x16_bf16 v[34:49], v[34:37], v[50:53], 0
	s_waitcnt vmcnt(2) lgkmcnt(1)
	v_mfma_f32_32x32x16_bf16 v[34:49], v[152:155], v[54:57], v[34:49]
	ds_read_b128 v[152:155], v160
	v_add_u32_e32 v210, v149, v197
	v_add_u32_e32 v211, v150, v197
	ds_read2_b64 v[216:219], v210 offset1:2
	ds_read2_b64 v[220:223], v211 offset1:2
	ds_read2_b64 v[224:227], v210 offset0:4 offset1:6
	ds_read2_b64 v[228:231], v211 offset0:4 offset1:6
	s_waitcnt vmcnt(1) lgkmcnt(5)
	v_mfma_f32_32x32x16_bf16 v[34:49], v[156:159], v[58:61], v[34:49]
	s_waitcnt vmcnt(0) lgkmcnt(4)
	v_mfma_f32_32x32x16_bf16 v[34:49], v[152:155], v[62:65], v[34:49]
	s_add_i32 s8, s8, 32
	v_add_u32_e32 v150, 64, v150
	v_add_u32_e32 v149, 64, v149
	v_add_u32_e32 v148, 0x1000, v148
	v_add_u32_e32 v147, 0x1000, v147
	v_add_u32_e32 v91, 0x1000, v91
	v_add_u32_e32 v90, 0x1000, v90
	s_nop 7
	v_max3_f32 v152, v34, s22, v35
	v_max3_f32 v152, v152, v36, v37
	v_max3_f32 v152, v152, v38, v39
	v_max3_f32 v152, v152, v40, v41
	v_max3_f32 v152, v152, v42, v43
	v_max3_f32 v152, v152, v44, v45
	v_max3_f32 v152, v152, v46, v47
	v_max3_f32 v152, v152, v48, v49
	v_mov_b32_e32 v156, v152
	s_nop 1
	v_permlane32_swap_b32_e32 v152, v156
	v_max_f32_e32 v152, v152, v156
	v_mul_f32_e32 v152, 0x3e38aa3b, v152
	v_max_f32_e32 v154, v0, v152
	v_sub_f32_e32 v0, v0, v154
	v_pk_fma_f32 v[34:35], v[34:35], s[22:23], v[154:155] op_sel:[0,1,0] op_sel_hi:[1,1,0] neg_lo:[0,0,1] neg_hi:[0,0,1]
	v_pk_fma_f32 v[36:37], v[36:37], s[22:23], v[154:155] op_sel:[0,1,0] op_sel_hi:[1,1,0] neg_lo:[0,0,1] neg_hi:[0,0,1]
	v_pk_fma_f32 v[38:39], v[38:39], s[22:23], v[154:155] op_sel:[0,1,0] op_sel_hi:[1,1,0] neg_lo:[0,0,1] neg_hi:[0,0,1]
	v_pk_fma_f32 v[40:41], v[40:41], s[22:23], v[154:155] op_sel:[0,1,0] op_sel_hi:[1,1,0] neg_lo:[0,0,1] neg_hi:[0,0,1]
	v_pk_fma_f32 v[42:43], v[42:43], s[22:23], v[154:155] op_sel:[0,1,0] op_sel_hi:[1,1,0] neg_lo:[0,0,1] neg_hi:[0,0,1]
	v_pk_fma_f32 v[44:45], v[44:45], s[22:23], v[154:155] op_sel:[0,1,0] op_sel_hi:[1,1,0] neg_lo:[0,0,1] neg_hi:[0,0,1]
	v_pk_fma_f32 v[46:47], v[46:47], s[22:23], v[154:155] op_sel:[0,1,0] op_sel_hi:[1,1,0] neg_lo:[0,0,1] neg_hi:[0,0,1]
	v_pk_fma_f32 v[48:49], v[48:49], s[22:23], v[154:155] op_sel:[0,1,0] op_sel_hi:[1,1,0] neg_lo:[0,0,1] neg_hi:[0,0,1]
	v_exp_f32_e32 v0, v0
	v_exp_f32_e32 v34, v34
	v_exp_f32_e32 v35, v35
	v_exp_f32_e32 v36, v36
	v_exp_f32_e32 v37, v37
	v_exp_f32_e32 v38, v38
	v_exp_f32_e32 v39, v39
	v_exp_f32_e32 v40, v40
	v_exp_f32_e32 v41, v41
	v_exp_f32_e32 v42, v42
	v_exp_f32_e32 v43, v43
	v_exp_f32_e32 v44, v44
	v_exp_f32_e32 v45, v45
	v_exp_f32_e32 v46, v46
	v_exp_f32_e32 v47, v47
	v_exp_f32_e32 v48, v48
	v_exp_f32_e32 v49, v49
	s_nop 0
	v_pk_add_f32 v[232:233], v[34:35], v[36:37]
	v_pk_add_f32 v[234:235], v[38:39], v[40:41]
	v_pk_add_f32 v[236:237], v[42:43], v[44:45]
	v_pk_add_f32 v[238:239], v[46:47], v[48:49]
	v_pk_add_f32 v[232:233], v[232:233], v[234:235]
	v_pk_add_f32 v[236:237], v[236:237], v[238:239]
	v_pk_add_f32 v[232:233], v[232:233], v[236:237]
	v_add_f32_e32 v240, v232, v233
	v_mov_b32_e32 v241, v240
	s_nop 1
	v_permlane32_swap_b32_e32 v240, v241
	v_mov_b32_e32 v71, v154
	v_cvt_pk_bf16_f32 v156, v34, v35
	v_cvt_pk_bf16_f32 v157, v36, v37
	v_cvt_pk_bf16_f32 v158, v38, v39
	v_cvt_pk_bf16_f32 v159, v40, v41
	v_cvt_pk_bf16_f32 v152, v42, v43
	v_cvt_pk_bf16_f32 v153, v44, v45
	v_cvt_pk_bf16_f32 v154, v46, v47
	v_cvt_pk_bf16_f32 v155, v48, v49
	v_add_f32_e32 v36, v240, v241
	v_fmac_f32_e32 v36, v151, v0
	v_cmp_neq_f32_e32 vcc, 1.0, v0
	s_cbranch_vccz .Lattn_fkeep_790
	v_pk_mul_f32 v[32:33], v[32:33], v[0:1] op_sel_hi:[1,0]
	v_pk_mul_f32 v[30:31], v[30:31], v[0:1] op_sel_hi:[1,0]
	v_pk_mul_f32 v[28:29], v[28:29], v[0:1] op_sel_hi:[1,0]
	v_pk_mul_f32 v[26:27], v[26:27], v[0:1] op_sel_hi:[1,0]
	v_pk_mul_f32 v[24:25], v[24:25], v[0:1] op_sel_hi:[1,0]
	v_pk_mul_f32 v[22:23], v[22:23], v[0:1] op_sel_hi:[1,0]
	v_pk_mul_f32 v[20:21], v[20:21], v[0:1] op_sel_hi:[1,0]
	v_pk_mul_f32 v[18:19], v[18:19], v[0:1] op_sel_hi:[1,0]
	v_pk_mul_f32 v[16:17], v[16:17], v[0:1] op_sel_hi:[1,0]
	v_pk_mul_f32 v[14:15], v[14:15], v[0:1] op_sel_hi:[1,0]
	v_pk_mul_f32 v[12:13], v[12:13], v[0:1] op_sel_hi:[1,0]
	v_pk_mul_f32 v[10:11], v[10:11], v[0:1] op_sel_hi:[1,0]
	v_pk_mul_f32 v[8:9], v[8:9], v[0:1] op_sel_hi:[1,0]
	v_pk_mul_f32 v[6:7], v[6:7], v[0:1] op_sel_hi:[1,0]
	v_pk_mul_f32 v[4:5], v[4:5], v[0:1] op_sel_hi:[1,0]
	v_pk_mul_f32 v[2:3], v[2:3], v[0:1] op_sel_hi:[1,0]
.Lattn_fkeep_790:
	s_waitcnt lgkmcnt(0)
	v_mfma_f32_32x32x16_bf16 v[18:33], v[216:219], v[156:159], v[18:33]
	v_mfma_f32_32x32x16_bf16 v[2:17], v[220:223], v[156:159], v[2:17]
	s_cmpk_eq_i32 s8, 0x100
	v_mfma_f32_32x32x16_bf16 v[18:33], v[224:227], v[152:155], v[18:33]
	v_mfma_f32_32x32x16_bf16 v[2:17], v[228:231], v[152:155], v[2:17]
	s_cbranch_scc1 .LBB0_798
	v_mov_b32_e32 v151, v36
	s_branch .LBB0_790
